# indexer sweeps A/B: loop-top wait relaxed to vmcnt only (LDS atomics/writes need no completion wait)
# speedup vs baseline: 1.0052x; 1.0001x over previous
; DI void attn_item(const Params& P, unsigned char* smem, bool samp, int b, int c) {
;     ...
;     for (int kt = 0; kt < ntiles; ++kt) {
;       float sc[4][2];
;       IDX_PIPE_STEP(kt, sc);
.LBB0_300:
	s_waitcnt vmcnt(0)
	v_mfma_f32_32x32x16_bf16 v[20:35], v[44:47], v[68:71], 0
	s_cmp_ge_u32 s14, s95
	v_mfma_f32_32x32x16_bf16 v[4:19], v[44:47], v[84:87], 0
	v_mfma_f32_32x32x16_bf16 v[20:35], v[36:39], v[92:95], v[20:35]
	v_mfma_f32_32x32x16_bf16 v[4:19], v[36:39], v[72:75], v[4:19]
	v_mfma_f32_32x32x16_bf16 v[20:35], v[40:43], v[80:83], v[20:35]
	v_mfma_f32_32x32x16_bf16 v[4:19], v[40:43], v[88:91], v[4:19]
	v_mfma_f32_32x32x16_bf16 v[20:35], v[48:51], v[96:99], v[20:35]
	v_mfma_f32_32x32x16_bf16 v[4:19], v[48:51], v[76:79], v[4:19]
	s_cbranch_scc1 .LBB0_302
	v_lshl_add_u64 v[68:69], v[114:115], 0, s[2:3]
	v_add_co_u32_e32 v76, vcc, 0x2000, v68
	s_nop 1
	v_addc_co_u32_e32 v77, vcc, 0, v69, vcc
	v_add_co_u32_e32 v78, vcc, 0x3000, v68
	s_nop 1
	v_addc_co_u32_e32 v79, vcc, 0, v69, vcc
	global_load_dwordx4 v[68:71], v[76:77], off
	global_load_dwordx4 v[92:95], v[76:77], off offset:1024
	global_load_dwordx4 v[84:87], v[78:79], off
	global_load_dwordx4 v[72:75], v[78:79], off offset:1024
	global_load_dwordx4 v[80:83], v[76:77], off offset:2048
	global_load_dwordx4 v[96:99], v[76:77], off offset:3072
	global_load_dwordx4 v[88:91], v[78:79], off offset:2048
	s_nop 0
	global_load_dwordx4 v[76:79], v[78:79], off offset:3072

; DI void attn_item(const Params& P, unsigned char* smem, bool samp, int b, int c) {
;     ...
;       for (int kt = 0; kt < ntiles; ++kt) {
;         float sc[4][2];
;         IDX_PIPE_STEP(kt, sc);
.LBB0_618:
	s_waitcnt vmcnt(0)
	v_mfma_f32_32x32x16_bf16 v[20:35], v[44:47], v[76:79], 0
	s_add_i32 s96, s96, 1
	s_cmp_ge_u32 s96, s95
	v_mfma_f32_32x32x16_bf16 v[4:19], v[44:47], v[80:83], 0
	v_mfma_f32_32x32x16_bf16 v[20:35], v[36:39], v[88:91], v[20:35]
	v_mfma_f32_32x32x16_bf16 v[4:19], v[36:39], v[84:87], v[4:19]
	v_mfma_f32_32x32x16_bf16 v[20:35], v[40:43], v[92:95], v[20:35]
	v_mfma_f32_32x32x16_bf16 v[4:19], v[40:43], v[96:99], v[4:19]
	v_mfma_f32_32x32x16_bf16 v[20:35], v[48:51], v[104:107], v[20:35]
	v_mfma_f32_32x32x16_bf16 v[4:19], v[48:51], v[100:103], v[4:19]
	s_cbranch_scc1 .LBB0_620
	v_add_co_u32_e32 v76, vcc, 0xffffe400, v116
	s_nop 1
	v_addc_co_u32_e32 v77, vcc, -1, v117, vcc
	v_add_co_u32_e32 v80, vcc, 0xfffff400, v116
	s_nop 1
	v_addc_co_u32_e32 v81, vcc, -1, v117, vcc
	v_add_co_u32_e32 v84, vcc, 0xffffe800, v116
	global_load_dwordx4 v[76:79], v[76:77], off
	s_nop 0
	global_load_dwordx4 v[80:83], v[80:81], off
	v_addc_co_u32_e32 v85, vcc, -1, v117, vcc
	v_add_co_u32_e32 v86, vcc, 0xfffff800, v116
	s_nop 1
	v_addc_co_u32_e32 v87, vcc, -1, v117, vcc
	v_add_co_u32_e32 v92, vcc, 0xffffec00, v116
	global_load_dwordx4 v[88:91], v[84:85], off
	s_nop 0
	global_load_dwordx4 v[84:87], v[86:87], off
	v_addc_co_u32_e32 v93, vcc, -1, v117, vcc
	v_add_co_u32_e32 v96, vcc, 0xfffffc00, v116
	s_nop 1
	v_addc_co_u32_e32 v97, vcc, -1, v117, vcc
	v_add_co_u32_e32 v100, vcc, 0xfffff000, v116
	global_load_dwordx4 v[92:95], v[92:93], off
	s_nop 0
	global_load_dwordx4 v[96:99], v[96:97], off
	v_addc_co_u32_e32 v101, vcc, -1, v117, vcc
	global_load_dwordx4 v[104:107], v[100:101], off
	s_nop 0
	global_load_dwordx4 v[100:103], v[116:117], off
